# s_setprio 1 for waves 4-7 scoped to gate/up, down and proj GEMM phases only (reset before the next non-GEMM phase)
# baseline (speedup 1.0000x reference)
.LBB0_290:
	s_or_b64 exec, exec, s[2:3]
	v_readfirstlane_b32 s32, v178
	s_nop 3
	s_cmp_lt_u32 s32, 0x100
	s_cbranch_scc1 .Lgprio_skip1
	s_setprio 1
.Lgprio_skip1:
	s_cmp_eq_u32 s50, 0
	s_mov_b64 s[2:3], s[66:67]
	s_mov_b32 s26, s70
	s_mov_b32 s27, s68
	v_mov_b32_e32 v10, v178
	s_cselect_b64 s[10:11], -1, 0
	s_waitcnt lgkmcnt(0)
	s_barrier
	s_cmpk_gt_i32 s27, 0xaff
	v_readfirstlane_b32 s28, v10
	s_cbranch_scc1 .LBB0_302
	v_lshlrev_b32_e32 v1, 4, v10
	v_add_u32_e32 v2, 0x2000, v1
	v_ashrrev_i32_e32 v3, 31, v2
	v_lshrrev_b32_e32 v3, 22, v3
	v_add_u32_e32 v3, v2, v3
	v_ashrrev_i32_e32 v11, 10, v3
	s_load_dwordx2 s[2:3], s[2:3], 0x120
	v_mul_i32_i24_e32 v3, 0x400, v11
	v_sub_u32_e32 v2, v2, v3
	v_lshrrev_b32_e32 v3, 4, v2
	v_bitop3_b32 v2, v3, v2, 32 bitop3:0x6c
	v_ashrrev_i32_e32 v3, 31, v2
	s_waitcnt lgkmcnt(0)
	s_add_u32 s29, s2, 0x15200000
	v_lshrrev_b32_e32 v3, 26, v3
	s_addc_u32 s30, s3, 0
	v_add_u32_e32 v3, v2, v3
	v_lshlrev_b32_e32 v4, 3, v11
	s_and_b64 s[4:5], s[10:11], exec
	v_ashrrev_i32_e32 v12, 6, v3
	v_and_b32_e32 v4, -16, v4
	s_cselect_b32 s4, 0, 0xb00000
	v_add_u32_e32 v4, v12, v4
	s_add_u32 s31, s2, s4
	v_and_b32_e32 v5, 3, v12
	s_mov_b32 s4, 0x1fffe0
	v_lshrrev_b32_e32 v6, 2, v4
	v_lshlrev_b32_e32 v7, 1, v4
	v_and_b32_e32 v3, 0xc0, v3
	v_and_or_b32 v5, v4, s4, v5
	v_and_b32_e32 v6, 4, v6
	v_and_b32_e32 v7, 24, v7
	v_sub_u32_e32 v2, v2, v3
	v_or3_b32 v5, v5, v6, v7
	v_lshlrev_b32_e32 v6, 5, v11
	v_ashrrev_i16_sdwa v2, v254, sext(v2) dst_sel:DWORD dst_unused:UNUSED_PAD src0_sel:DWORD src1_sel:BYTE_0
	v_and_b32_e32 v6, 32, v6
	v_bfe_i32 v13, v2, 0, 16
	v_add_lshl_u32 v2, v6, v13, 1
	v_lshl_add_u32 v130, v5, 11, v2
	v_lshl_add_u32 v132, v4, 11, v2
	v_bfe_i32 v2, v10, 27, 1
	v_lshrrev_b32_e32 v2, 22, v2
	v_add_u32_e32 v2, v1, v2
	v_and_b32_e32 v2, 0xfffffc00, v2
	v_sub_u32_e32 v1, v1, v2
	v_lshrrev_b32_e32 v2, 4, v1
	v_bitop3_b32 v2, v2, v1, 32 bitop3:0x6c
	v_ashrrev_i32_e32 v1, 31, v1
	v_lshrrev_b32_e32 v1, 26, v1
	v_add_u32_e32 v1, v2, v1
	v_ashrrev_i32_e32 v14, 6, v1
	v_ashrrev_i32_e32 v1, 31, v10
	v_lshrrev_b32_e32 v1, 26, v1
	v_add_u32_e32 v1, v10, v1
	v_ashrrev_i32_e32 v15, 6, v1
	v_lshlrev_b32_e32 v1, 3, v15
	v_and_b32_e32 v1, -16, v1
	s_addc_u32 s33, s3, 0
	s_ashr_i32 s34, s27, 31
	v_add_u32_e32 v1, v14, v1
	v_and_b32_e32 v3, 3, v14
	v_and_or_b32 v3, v1, s4, v3
	s_lshr_b32 s4, s34, 29
	s_add_i32 s4, s27, s4
	s_ashr_i32 s6, s28, 6
	s_ashr_i32 s7, s4, 3
	s_and_b32 s4, s4, -8
	s_ashr_i32 s5, s28, 8
	s_lshl_b32 s35, s6, 10
	s_sub_i32 s4, s27, s4
	s_cmp_lt_i32 s4, 0
	s_movk_i32 s8, 0x161
	s_cselect_b32 s8, s8, 0x160
	s_mul_i32 s4, s8, s4
	s_add_i32 s4, s4, s7
	s_mul_hi_i32 s7, s4, 0x2e8ba2e9
	s_lshr_b32 s8, s7, 31
	s_ashr_i32 s7, s7, 5
	s_add_i32 s7, s7, s8
	s_lshl_b32 s8, s7, 3
	s_mulk_i32 s7, 0xb0
	s_sub_i32 s7, s4, s7
	s_bfe_u32 s4, s7, 0x3001c
	s_add_i32 s9, s7, s4
	s_sext_i32_i16 s4, s9
	s_and_b32 s9, s9, 0xfff8
	v_lshrrev_b32_e32 v4, 2, v1
	v_lshlrev_b32_e32 v5, 1, v1
	s_sub_i32 s7, s7, s9
	v_and_b32_e32 v4, 4, v4
	v_and_b32_e32 v5, 24, v5
	s_sext_i32_i16 s7, s7
	v_or3_b32 v3, v3, v4, v5
	v_mul_i32_i24_e32 v5, 64, v14
	s_lshr_b32 s4, s4, 3
	s_add_i32 s18, s8, s7
	v_sub_u32_e32 v2, v2, v5
	s_ashr_i32 s19, s18, 31
	s_bfe_i64 s[12:13], s[4:5], 0x100000
	v_lshlrev_b32_e32 v4, 5, v15
	v_ashrrev_i16_sdwa v2, v254, sext(v2) dst_sel:DWORD dst_unused:UNUSED_PAD src0_sel:DWORD src1_sel:BYTE_0
	s_lshl_b64 s[8:9], s[18:19], 19
	s_lshl_b64 s[12:13], s[12:13], 19
	v_and_b32_e32 v4, 32, v4
	v_bfe_i32 v16, v2, 0, 16
	s_add_u32 s22, s31, s12
	v_add_lshl_u32 v2, v4, v16, 1
	s_addc_u32 s23, s33, s13
	s_add_i32 s19, s35, 0
	v_lshl_add_u32 v134, v3, 11, v2
	s_add_i32 m0, s19, 0x10000
	v_lshl_add_u32 v136, v1, 11, v2
	global_load_lds_dwordx4 v134, s[22:23]
	s_add_i32 m0, s19, 0x12000
	s_add_u32 s20, s29, s8
	global_load_lds_dwordx4 v130, s[22:23]
	s_addc_u32 s21, s30, s9
	s_mov_b32 m0, s19
	s_add_i32 s36, s19, 0x2000
	global_load_lds_dwordx4 v136, s[20:21]
	s_mov_b32 m0, s36
	s_add_u32 s8, s22, 0x40000
	global_load_lds_dwordx4 v132, s[20:21]
	s_addc_u32 s9, s23, 0
	s_add_i32 m0, s19, 0x14000
	v_mov_b32_e32 v135, v0
	global_load_lds_dwordx4 v134, s[8:9]
	s_add_i32 m0, s19, 0x16000
	v_mov_b32_e32 v131, v0
	global_load_lds_dwordx4 v130, s[8:9]
	s_add_u32 s8, s20, 0x40000
	s_addc_u32 s9, s21, 0
	s_add_i32 s37, s19, 0x4000
	s_mov_b32 m0, s37
	s_add_i32 s38, s19, 0x6000
	global_load_lds_dwordx4 v136, s[8:9]
	s_mov_b32 m0, s38
	v_mov_b32_e32 v137, v0
	global_load_lds_dwordx4 v132, s[8:9]
	v_mov_b32_e32 v133, v0
	v_lshl_add_u64 v[8:9], s[22:23], 0, v[134:135]
	v_lshl_add_u64 v[6:7], s[22:23], 0, v[130:131]
	v_lshl_add_u64 v[4:5], s[20:21], 0, v[136:137]
	s_cmp_lg_u32 s5, 1
	v_lshl_add_u64 v[2:3], s[20:21], 0, v[132:133]
	s_cbranch_scc1 .LBB0_293
	s_barrier

.Lgprio_skip2:
	v_readlane_b32 s6, v255, 31
	s_cmp_gt_u32 s6, 1
	s_cselect_b64 s[2:3], -1, 0
	s_cmp_lt_u32 s6, 2
	s_cselect_b64 s[8:9], -1, 0
	s_and_b64 s[6:7], s[8:9], exec
	s_cselect_b32 s6, 19, 16
	s_movk_i32 s7, 0x1200
	s_mov_b64 s[4:5], s[66:67]
	s_cselect_b32 s7, s7, 0x1000
	s_mov_b32 s26, s70
	s_mov_b32 s27, s68
	v_mov_b32_e32 v16, v178
	s_lshl_b32 s80, s6, 7
	s_waitcnt lgkmcnt(0)
	s_barrier
	v_writelane_b32 v255, s7, 32
	s_cmp_ge_i32 s27, s80
	v_readfirstlane_b32 s28, v16
	s_cbranch_scc1 .LBB0_537
	v_lshlrev_b32_e32 v1, 4, v16
	v_add_u32_e32 v2, 0x2000, v1
	v_ashrrev_i32_e32 v3, 31, v2
	v_lshrrev_b32_e32 v3, 22, v3
	v_add_u32_e32 v3, v2, v3
	v_ashrrev_i32_e32 v10, 10, v3
	v_mul_i32_i24_e32 v3, 0x400, v10
	v_sub_u32_e32 v2, v2, v3
	v_lshrrev_b32_e32 v3, 4, v2
	v_bitop3_b32 v2, v3, v2, 32 bitop3:0x6c
	v_ashrrev_i32_e32 v3, 31, v2
	v_lshrrev_b32_e32 v3, 26, v3
	v_add_u32_e32 v3, v2, v3
	v_lshlrev_b32_e32 v4, 3, v10
	v_ashrrev_i32_e32 v11, 6, v3
	v_and_b32_e32 v4, -16, v4
	v_add_u32_e32 v4, v11, v4
	v_and_b32_e32 v5, 3, v11
	s_mov_b32 s7, 0x1fffe0
	v_lshrrev_b32_e32 v6, 2, v4
	v_lshlrev_b32_e32 v7, 1, v4
	v_and_b32_e32 v3, 0xc0, v3
	v_and_or_b32 v5, v4, s7, v5
	v_and_b32_e32 v6, 4, v6
	v_and_b32_e32 v7, 24, v7
	v_sub_u32_e32 v2, v2, v3
	v_or3_b32 v5, v5, v6, v7
	v_lshlrev_b32_e32 v6, 5, v10
	v_ashrrev_i16_sdwa v2, v254, sext(v2) dst_sel:DWORD dst_unused:UNUSED_PAD src0_sel:DWORD src1_sel:BYTE_0
	v_and_b32_e32 v6, 32, v6
	v_bfe_i32 v12, v2, 0, 16
	v_add_lshl_u32 v2, v6, v12, 1
	v_lshl_add_u32 v130, v5, 11, v2
	v_lshl_add_u32 v132, v4, 11, v2
	v_bfe_i32 v2, v16, 27, 1
	v_lshrrev_b32_e32 v2, 22, v2
	v_add_u32_e32 v2, v1, v2
	v_and_b32_e32 v2, 0xfffffc00, v2
	v_sub_u32_e32 v1, v1, v2
	v_lshrrev_b32_e32 v2, 4, v1
	v_bitop3_b32 v2, v2, v1, 32 bitop3:0x6c
	v_ashrrev_i32_e32 v1, 31, v1
	v_lshrrev_b32_e32 v1, 26, v1
	v_add_u32_e32 v1, v2, v1
	v_ashrrev_i32_e32 v13, 6, v1
	v_ashrrev_i32_e32 v1, 31, v16
	v_lshrrev_b32_e32 v1, 26, v1
	v_add_u32_e32 v1, v16, v1
	v_ashrrev_i32_e32 v14, 6, v1
	s_load_dwordx2 s[4:5], s[4:5], 0x120
	v_lshlrev_b32_e32 v1, 3, v14
	v_and_b32_e32 v1, -16, v1
	v_add_u32_e32 v1, v13, v1
	v_and_b32_e32 v3, 3, v13
	v_lshrrev_b32_e32 v4, 2, v1
	v_lshlrev_b32_e32 v5, 1, v1
	v_and_or_b32 v3, v1, s7, v3
	v_and_b32_e32 v4, 4, v4
	v_and_b32_e32 v5, 24, v5
	s_waitcnt lgkmcnt(0)
	s_add_u32 s29, s4, 0x15200000
	v_or3_b32 v3, v3, v4, v5
	v_mul_i32_i24_e32 v5, 64, v13
	s_addc_u32 s30, s5, 0
	v_sub_u32_e32 v2, v2, v5
	s_add_u32 s31, s4, 0x2100000
	v_lshlrev_b32_e32 v4, 5, v14
	v_ashrrev_i16_sdwa v2, v254, sext(v2) dst_sel:DWORD dst_unused:UNUSED_PAD src0_sel:DWORD src1_sel:BYTE_0
	s_addc_u32 s33, s5, 0
	v_and_b32_e32 v4, 32, v4
	v_bfe_i32 v15, v2, 0, 16
	s_lshl_b32 s37, s6, 3
	v_add_lshl_u32 v2, v4, v15, 1
	s_abs_i32 s38, s37
	v_lshl_add_u32 v136, v1, 11, v2
	v_cvt_f32_u32_e32 v1, s38
	s_ashr_i32 s34, s27, 31
	s_lshr_b32 s7, s34, 29
	s_add_i32 s7, s27, s7
	v_rcp_iflag_f32_e32 v1, v1
	s_ashr_i32 s10, s7, 3
	s_and_b32 s7, s7, -8
	s_sub_i32 s7, s27, s7
	v_mul_f32_e32 v1, 0x4f7ffffe, v1
	v_cvt_u32_f32_e32 v1, v1
	s_lshl_b32 s36, s6, 4
	s_lshr_b32 s11, s7, 31
	s_or_b32 s11, s11, s36
	s_mul_i32 s7, s11, s7
	s_sub_i32 s11, 0, s38
	v_readfirstlane_b32 s40, v1
	s_add_i32 s7, s7, s10
	s_mul_i32 s11, s11, s40
	s_ashr_i32 s10, s7, 31
	s_bfe_i32 s39, s6, 0x1001c
	s_mul_hi_u32 s11, s40, s11
	s_xor_b32 s6, s10, s39
	s_abs_i32 s10, s7
	s_add_i32 s40, s40, s11
	s_mul_hi_u32 s11, s10, s40
	s_mul_i32 s14, s11, s38
	s_ashr_i32 s13, s28, 6
	s_sub_i32 s10, s10, s14
	s_ashr_i32 s12, s28, 8
	s_lshl_b32 s35, s13, 10
	s_add_i32 s14, s11, 1
	s_sub_i32 s15, s10, s38
	s_cmp_ge_u32 s10, s38
	s_cselect_b32 s11, s14, s11
	s_cselect_b32 s10, s15, s10
	s_add_i32 s14, s11, 1
	s_cmp_ge_u32 s10, s38
	s_cselect_b32 s10, s14, s11
	s_xor_b32 s10, s10, s6
	s_sub_i32 s6, s10, s6
	s_lshl_b32 s10, s6, 3
	s_sub_i32 s11, 0x80, s10
	s_min_i32 s11, s11, 8
	v_cvt_f32_i32_e32 v1, s11
	s_mul_i32 s6, s6, s37
	s_sub_i32 s14, s7, s6
	v_lshl_add_u32 v134, v3, 11, v2
	v_cvt_f32_i32_e32 v2, s14
	v_rcp_iflag_f32_e32 v3, v1
	s_xor_b32 s6, s14, s11
	s_ashr_i32 s6, s6, 30
	s_or_b32 s15, s6, 1
	v_mul_f32_e32 v3, v2, v3
	v_trunc_f32_e32 v3, v3
	v_fma_f32 v2, -v3, v1, v2
	v_cvt_i32_f32_e32 v3, v3
	v_cmp_ge_f32_e64 s[6:7], |v2|, |v1|
	s_and_b64 s[6:7], s[6:7], exec
	s_cselect_b32 s6, s15, 0
	v_readfirstlane_b32 s7, v3
	s_add_i32 s6, s7, s6
	s_mul_i32 s7, s6, s11
	s_sub_i32 s7, s14, s7
	s_sext_i32_i16 s7, s7
	s_add_i32 s10, s10, s7
	s_ashr_i32 s11, s10, 31
	s_bfe_i64 s[16:17], s[6:7], 0x100000
	s_lshl_b64 s[14:15], s[10:11], 19
	s_lshl_b64 s[16:17], s[16:17], 19
	s_add_u32 s22, s31, s16
	s_addc_u32 s23, s33, s17
	s_add_i32 s41, s35, 0
	s_add_i32 m0, s41, 0x10000
	v_mov_b32_e32 v135, v0
	global_load_lds_dwordx4 v134, s[22:23]
	s_add_i32 m0, s41, 0x12000
	s_add_u32 s20, s29, s14
	global_load_lds_dwordx4 v130, s[22:23]
	s_addc_u32 s21, s30, s15
	s_mov_b32 m0, s41
	s_add_i32 s42, s41, 0x2000
	global_load_lds_dwordx4 v136, s[20:21]
	s_mov_b32 m0, s42
	s_add_u32 s14, s22, 0x40000
	global_load_lds_dwordx4 v132, s[20:21]
	s_addc_u32 s15, s23, 0
	s_add_i32 m0, s41, 0x14000
	v_mov_b32_e32 v131, v0
	global_load_lds_dwordx4 v134, s[14:15]
	s_add_i32 m0, s41, 0x16000
	v_mov_b32_e32 v137, v0
	global_load_lds_dwordx4 v130, s[14:15]
	s_add_u32 s14, s20, 0x40000
	s_addc_u32 s15, s21, 0
	s_add_i32 s43, s41, 0x4000
	s_mov_b32 m0, s43
	s_add_i32 s44, s41, 0x6000
	global_load_lds_dwordx4 v136, s[14:15]
	s_mov_b32 m0, s44
	v_mov_b32_e32 v133, v0
	global_load_lds_dwordx4 v132, s[14:15]
	v_lshl_add_u64 v[8:9], s[22:23], 0, v[134:135]
	v_lshl_add_u64 v[6:7], s[22:23], 0, v[130:131]
	v_lshl_add_u64 v[4:5], s[20:21], 0, v[136:137]
	s_cmp_lg_u32 s12, 1
	v_lshl_add_u64 v[2:3], s[20:21], 0, v[132:133]
	s_cbranch_scc1 .LBB0_522
	s_barrier
